# XCD-locality verdict computed at barrier 3's entry (off the post-barrier critical path); rest as best
# speedup vs baseline: 1.0015x; 1.0015x over previous
.LBB0_340:
	v_mov_b32_e32 v0, 0
	s_add_u32 s98, s66, 0x40000
	s_addc_u32 s99, s67, 0
	s_nop 0
	global_load_dwordx4 v[4:7], v0, s[98:99] offset:32 sc1
	global_load_dwordx4 v[8:11], v0, s[98:99] offset:48 sc1
	s_mov_b32 s100, 1
	s_waitcnt vmcnt(0)
	v_readfirstlane_b32 s101, v4
	s_bcnt1_i32_b32 s101, s101
	s_cmp_eq_u32 s101, 1
	s_cselect_b32 s100, s100, 0
	v_readfirstlane_b32 s101, v5
	s_bcnt1_i32_b32 s101, s101
	s_cmp_eq_u32 s101, 1
	s_cselect_b32 s100, s100, 0
	v_readfirstlane_b32 s101, v6
	s_bcnt1_i32_b32 s101, s101
	s_cmp_eq_u32 s101, 1
	s_cselect_b32 s100, s100, 0
	v_readfirstlane_b32 s101, v7
	s_bcnt1_i32_b32 s101, s101
	s_cmp_eq_u32 s101, 1
	s_cselect_b32 s100, s100, 0
	v_readfirstlane_b32 s101, v8
	s_bcnt1_i32_b32 s101, s101
	s_cmp_eq_u32 s101, 1
	s_cselect_b32 s100, s100, 0
	v_readfirstlane_b32 s101, v9
	s_bcnt1_i32_b32 s101, s101
	s_cmp_eq_u32 s101, 1
	s_cselect_b32 s100, s100, 0
	v_readfirstlane_b32 s101, v10
	s_bcnt1_i32_b32 s101, s101
	s_cmp_eq_u32 s101, 1
	s_cselect_b32 s100, s100, 0
	v_readfirstlane_b32 s101, v11
	s_bcnt1_i32_b32 s101, s101
	s_cmp_eq_u32 s101, 1
	s_cselect_b32 s100, s100, 0
	v_writelane_b32 v255, s100, 0
	v_mbcnt_lo_u32_b32 v0, -1, 0
	v_mbcnt_hi_u32_b32 v0, -1, v0
	s_waitcnt vmcnt(0)
	v_readlane_b32 s0, v254, 6
	v_sub_u32_e32 v0, 0, v0
	s_waitcnt vmcnt(0) lgkmcnt(0)
	v_cmp_eq_u32_e32 vcc, s0, v0
	s_barrier
	s_and_saveexec_b64 s[0:1], vcc
	v_readlane_b32 s84, v254, 18
	v_readlane_b32 s85, v254, 19
	s_cbranch_execz .LBB0_392
	s_add_i32 s4, 0, 0x20400
	v_mov_b32_e32 v0, s4
	s_waitcnt vmcnt(0) expcnt(0) lgkmcnt(0)
	ds_read_b32 v2, v0
	s_add_i32 s4, 0, 0x20404
	v_mov_b32_e32 v0, s4
	ds_read_b32 v0, v0
	s_waitcnt lgkmcnt(1)
	v_cmp_ne_u32_e32 vcc, 0, v2
	s_cbranch_vccnz .LBB0_356
	s_add_u32 s4, s66, 0x40200
	s_addc_u32 s5, s67, 0
	s_add_u32 s8, s66, 0x40400
	s_addc_u32 s9, s67, 0
	s_add_u32 s10, s66, 0x40500
	s_addc_u32 s11, s67, 0
	s_add_u32 s12, s66, 0x40600
	s_addc_u32 s13, s67, 0
	s_add_u32 s14, s66, 0x40700
	s_addc_u32 s15, s67, 0
	s_add_u32 s16, s66, 0x40800
	s_addc_u32 s17, s67, 0
	s_add_u32 s22, s66, 0x40900
	s_addc_u32 s23, s67, 0
	s_add_u32 s24, s66, 0x40a00
	s_addc_u32 s25, s67, 0
	s_add_u32 s42, s66, 0x40b00
	s_addc_u32 s43, s67, 0
	s_add_u32 s44, s66, 0x40c00
	s_addc_u32 s45, s67, 0
	s_add_u32 s46, s66, 0x40d00
	s_addc_u32 s47, s67, 0
	s_add_u32 s50, s66, 0x40e00
	s_addc_u32 s51, s67, 0
	s_add_u32 s52, s66, 0x40f00
	s_addc_u32 s53, s67, 0
	s_add_u32 s54, s66, 0x41000
	s_addc_u32 s55, s67, 0
	s_add_u32 s56, s66, 0x41100
	s_addc_u32 s57, s67, 0
	s_add_u32 s58, s66, 0x41200
	s_addc_u32 s59, s67, 0
	s_add_u32 s60, s66, 0x41300
	s_addc_u32 s61, s67, 0
	s_mov_b32 s20, 1
	v_mov_b32_e32 v16, 0
	s_branch .LBB0_344

.LBB0_392:
	s_or_b64 exec, exec, s[0:1]
	v_readlane_b32 s100, v255, 0
	s_nop 3
	s_cmp_eq_u32 s100, 0
	s_cbranch_scc1 .Lxl_stag_done
	v_readlane_b32 s101, v254, 0
	s_nop 3
	s_cmp_eq_u32 s101, 0
	s_cbranch_scc1 .Lxl_stag_done
